# gen6: PV and row-sum MFMAs in the non-scaled f8f6f4 form (unit scales), merged LDS waits; same fp8/fp6 operands and f32 accumulate
# baseline (speedup 1.0000x reference)
; DEVINL void partialSM(f32x16& p0, f32x16& p1, float& m_reg, float& mn, float& alpha, int kvalid, int hi) {
;   constexpr float C = MLA_SCALE * 1.4426950408889634f;
;   if (kvalid < 64) {
; #pragma unroll
;     for (int r = 0; r < 16; ++r) { if (crow(r, hi) >= kvalid) p0[r] = -1e30f; if (32 + crow(r, hi) >= kvalid) p1[r] = -1e30f; }
;   }
;   float pmax = p0[0];
; #pragma unroll
;   for (int r = 1; r < 16; ++r) pmax = fmaxf(pmax, p0[r]);
; #pragma unroll
;   for (int r = 0; r < 16; ++r) pmax = fmaxf(pmax, p1[r]);
;   { auto rr = __builtin_amdgcn_permlane32_swap(__float_as_uint(pmax), __float_as_uint(pmax), false, false);
;     pmax = fmaxf(__uint_as_float(rr[0]), __uint_as_float(rr[1])); }
;   if (__builtin_expect(__all(pmax - m_reg <= THR / MLA_SCALE), 1)) { mn = m_reg; alpha = 1.f; }
;   else { mn = fmaxf(m_reg, pmax); alpha = __builtin_amdgcn_exp2f((m_reg - mn) * C); m_reg = mn; }
;   const float mnC = PSHIFT - mn * C;
;   const f32x2 C2 = {C, C}, M2 = {mnC, mnC};
; #pragma unroll
;   for (int r = 0; r < 16; r += 2) { f32x2 v = {p0[r], p0[r + 1]}; v = __builtin_elementwise_fma(v, C2, M2); p0[r] = v[0]; p0[r + 1] = v[1]; }
; #pragma unroll
; template <bool FUSE>
; DEVINL void qkt(f32x16& p0, f32x16& p1, const char* Ks, const i32x8* q8, int r32, int hi, f32x16& e1) {
;   p0 = f32x16{}; p1 = f32x16{};
;   const char* ka = Ks + hi * 1024 + r32 * 16; const char* kb = Ks + 4096 + hi * 512 + r32 * 8;
;   const char* ra = Ks + 6144 + hi * 1024 + r32 * 16; const char* rb = Ks + 6144 + 2048 + hi * 512 + r32 * 8;
;   u32x4 fa[3][2]; u32x2 fb[3][2];
;     ...
;   QK_LD(0, 0);
; #pragma unroll
;   for (int t = 0; t < 3; ++t) {
;     if (t + 1 < 3) QK_LD(t + 1, (t + 1) % 3);
;     const i32x8 a0 = mk6((int)fa[t][0][0], (int)fa[t][0][1], (int)fa[t][0][2], (int)fa[t][0][3], (int)fb[t][0][0], (int)fb[t][0][1]);
;     const i32x8 a1 = mk6((int)fa[t][1][0], (int)fa[t][1][1], (int)fa[t][1][2], (int)fa[t][1][3], (int)fb[t][1][0], (int)fb[t][1][1]);
;     p0 = MFMA6(a0, q8[t], p0);
;     if (FUSE) {
; #pragma unroll
;       for (int r = 0; r < 3; ++r) { const int rr = t * 6 + r; if (rr < 16) e1[rr] = __builtin_amdgcn_exp2f(e1[rr]); }
;     }
;     p1 = MFMA6(a1, q8[t], p1);
;     if (FUSE) {
; #pragma unroll
;       for (int r = 3; r < 6; ++r) { const int rr = t * 6 + r; if (rr < 16) e1[rr] = __builtin_amdgcn_exp2f(e1[rr]); }
;     }
;     SBAR();
;   }
.LBB0_559:
	s_or_b64 exec, exec, s[8:9]
	s_mul_i32 s8, s75, 0x208000
	s_add_u32 s14, s58, s8
	v_add_u32_e32 v0, 0x9000, v172
	s_addc_u32 s15, s59, 0
	v_readfirstlane_b32 s9, v0
	v_add_u32_e32 v2, 0xb000, v172
	v_lshl_add_u64 v[140:141], s[14:15], 0, v[138:139]
	s_mov_b32 m0, s9
	v_readfirstlane_b32 s9, v2
	global_load_lds_dwordx4 v[140:141], off
	v_lshl_add_u64 v[0:1], v[140:141], 0, s[48:49]
	s_mov_b32 m0, s9
	v_lshlrev_b32_e32 v170, 9, v48
	global_load_lds_dwordx4 v[0:1], off
	v_and_b32_e32 v0, 0x3fffffc0, v166
	v_lshl_add_u32 v171, v0, 2, s68
	v_add_u32_e32 v0, 0, v170
	v_lshlrev_b32_e32 v176, 3, v167
	v_lshlrev_b32_e32 v175, 4, v167
	v_add_u32_e32 v49, v0, v176
	v_add3_u32 v173, v0, v170, v175
	v_add_u32_e32 v0, 0x1000, v49
	s_waitcnt vmcnt(0)
	s_waitcnt vmcnt(0) lgkmcnt(0)
	s_barrier
	ds_read2_b64 v[4:7], v0 offset1:32
	ds_read_b128 v[50:53], v173 offset:2048
	ds_read_b128 v[56:59], v173 offset:2560
	ds_read2_b64 v[60:63], v0 offset0:128 offset1:160
	ds_read_b128 v[16:19], v173 offset:512
	ds_read_b128 v[0:3], v173
	s_waitcnt lgkmcnt(5)
	v_mov_b32_e32 v20, v6
	v_mov_b32_e32 v21, v7
	s_waitcnt lgkmcnt(0)
	v_mfma_scale_f32_32x32x64_f8f6f4 v[32:47], v[0:5], v[120:125], 0, v162, v143 op_sel_hi:[0,0,0] cbsz:2 blgp:2
	s_mov_b32 s12, s13
	s_mov_b32 s14, s13
	s_mov_b32 s15, s13
	s_mov_b32 s16, s13
	s_mov_b32 s17, s13
	s_mov_b32 s18, s13
	s_mov_b32 s19, s13
	v_mfma_scale_f32_32x32x64_f8f6f4 v[16:31], v[16:21], v[120:125], 0, v162, v143 op_sel_hi:[0,0,0] cbsz:2 blgp:2
	s_mov_b32 s20, s13
	s_mov_b32 s21, s13
	s_mov_b32 s22, s13
	s_mov_b32 s23, s13
	s_mov_b32 s24, s13
	s_mov_b32 s25, s13
	s_mov_b32 s26, s13
	s_mov_b32 s27, s13
	v_mov_b64_e32 v[0:1], s[12:13]
	v_and_b32_e32 v169, 63, v166
	v_lshlrev_b32_e32 v174, 10, v48
	s_mov_b32 s53, 4
	v_mov_b64_e32 v[2:3], s[14:15]
	v_mov_b64_e32 v[4:5], s[16:17]
	v_mov_b64_e32 v[6:7], s[18:19]
	v_mov_b64_e32 v[8:9], s[20:21]
	v_mov_b64_e32 v[10:11], s[22:23]
	v_mov_b64_e32 v[12:13], s[24:25]
	v_mov_b64_e32 v[14:15], s[26:27]
	v_mov_b32_e32 v54, v60
	v_mov_b32_e32 v55, v61
	v_mov_b32_e32 v60, v62
	v_mov_b32_e32 v61, v63
	v_add_u32_e32 v49, 0x2000, v49
	v_mfma_scale_f32_32x32x64_f8f6f4 v[32:47], v[50:55], v[126:131], v[32:47], v162, v143 op_sel_hi:[0,0,0] cbsz:2 blgp:2
	ds_read_b128 v[50:53], v173 offset:6144
	ds_read_b128 v[62:65], v173 offset:6656
	ds_read2_b64 v[66:69], v49 offset1:32
	v_mfma_scale_f32_32x32x64_f8f6f4 v[16:31], v[56:61], v[126:131], v[16:31], v162, v143 op_sel_hi:[0,0,0] cbsz:2 blgp:2
	s_waitcnt lgkmcnt(0)
	v_mov_b32_e32 v54, v66
	v_mov_b32_e32 v55, v67
	v_mov_b32_e32 v66, v68
	v_mov_b32_e32 v67, v69
	v_mfma_scale_f32_32x32x64_f8f6f4 v[32:47], v[50:55], v[132:137], v[32:47], v162, v143 op_sel_hi:[0,0,0] cbsz:2 blgp:2
	s_nop 0
	v_mfma_scale_f32_32x32x64_f8f6f4 v[16:31], v[62:67], v[132:137], v[16:31], v162, v143 op_sel_hi:[0,0,0] cbsz:2 blgp:2
	s_nop 9
	v_max_f32_e32 v49, v33, v33
	v_max_f32_e32 v50, v32, v32
	v_max_f32_e32 v49, v50, v49
	v_max3_f32 v49, v49, v34, v35
	v_max3_f32 v49, v49, v36, v37
	v_max3_f32 v49, v49, v38, v39
	v_max3_f32 v49, v49, v40, v41
	v_max3_f32 v49, v49, v42, v43
	v_max3_f32 v49, v49, v44, v45
	v_max3_f32 v49, v49, v46, v47
	v_max3_f32 v49, v49, v16, v17
	v_max3_f32 v49, v49, v18, v19
	v_max3_f32 v49, v49, v20, v21
	v_max3_f32 v49, v49, v22, v23
	v_max3_f32 v49, v49, v24, v25
	v_max3_f32 v49, v49, v26, v27
	v_max3_f32 v49, v49, v28, v29
	v_max3_f32 v49, v49, v30, v31
	v_mov_b32_e32 v50, v49
	s_nop 1
	v_permlane32_swap_b32_e32 v49, v50
	v_max_f32_e32 v50, v50, v50
	v_max_f32_e32 v49, v49, v49
	v_max_f32_e32 v49, v49, v50
	v_add_f32_e32 v50, 0x7149f2ca, v49
	v_max_f32_e32 v49, 0xf149f2ca, v49
	v_sub_f32_e32 v51, 0xf149f2ca, v49
	v_mul_f32_e32 v51, 1.0, v51
	v_cmp_ge_f32_e32 vcc, s69, v50
	v_exp_f32_e32 v51, v51
	s_cmp_eq_u64 vcc, exec
	s_cselect_b64 vcc, -1, 0
	v_cndmask_b32_e32 v181, v49, v163, vcc
	v_fmamk_f32 v50, v181, 0xbf800000, v164
	v_pk_fma_f32 v[32:33], v[32:33], s[50:51], v[50:51] op_sel_hi:[1,0,0]
	v_pk_fma_f32 v[34:35], v[34:35], s[50:51], v[50:51] op_sel_hi:[1,0,0]
	v_pk_fma_f32 v[36:37], v[36:37], s[50:51], v[50:51] op_sel_hi:[1,0,0]
	v_pk_fma_f32 v[38:39], v[38:39], s[50:51], v[50:51] op_sel_hi:[1,0,0]
	v_pk_fma_f32 v[40:41], v[40:41], s[50:51], v[50:51] op_sel_hi:[1,0,0]
	v_pk_fma_f32 v[42:43], v[42:43], s[50:51], v[50:51] op_sel_hi:[1,0,0]
	v_pk_fma_f32 v[44:45], v[44:45], s[50:51], v[50:51] op_sel_hi:[1,0,0]
	v_pk_fma_f32 v[46:47], v[46:47], s[50:51], v[50:51] op_sel_hi:[1,0,0]
	v_exp_f32_e32 v65, v32
	v_exp_f32_e32 v197, v33
	v_exp_f32_e32 v187, v34
	v_exp_f32_e32 v189, v35
	v_exp_f32_e32 v195, v36
	v_exp_f32_e32 v196, v37
	v_exp_f32_e32 v191, v38
	v_exp_f32_e32 v192, v39
	v_exp_f32_e32 v193, v40
	v_exp_f32_e32 v194, v41
	v_exp_f32_e32 v183, v42
	v_exp_f32_e32 v184, v43
	v_exp_f32_e32 v188, v44
	v_exp_f32_e32 v190, v45
	v_exp_f32_e32 v185, v46
	v_exp_f32_e32 v186, v47
	s_add_u32 s8, s30, s8
	v_cndmask_b32_e64 v179, v51, 1.0, vcc
	v_pk_fma_f32 v[148:149], v[30:31], s[50:51], v[50:51] op_sel_hi:[1,0,0]
	v_pk_fma_f32 v[150:151], v[28:29], s[50:51], v[50:51] op_sel_hi:[1,0,0]
	v_pk_fma_f32 v[152:153], v[26:27], s[50:51], v[50:51] op_sel_hi:[1,0,0]
	v_pk_fma_f32 v[154:155], v[24:25], s[50:51], v[50:51] op_sel_hi:[1,0,0]
; #define SBAR() __builtin_amdgcn_sched_barrier(0)
; #define ISSUE_K(j) do { const int _t = (j) < NT ? (j) : NT - 1; char* _d = K_lds + ((j) & 3) * SHM_K8; if (wid < 6) GLDS(K8 + (size_t)_t * 6144 + t16u, _d + tid16); \
;     if (wid < 3) GLDS(Kp8 + (size_t)_t * 3072 + t16u, _d + 6144 + tid16); } while (0)
; #define ISSUE_V(j) do { const int _t = (j) < NT ? (j) : NT - 1; GLDS(V8 + (size_t)_t * 8192 + t16u, V_lds + ((j) & 3) * SHM_V8 + tid16); } while (0)
; #define TILE_SYNC() do { asm volatile("s_waitcnt vmcnt(0)" ::: "memory"); __syncthreads(); } while (0)
; DEVINL void mla_block(const Params& p, const bf16_t* __restrict__ Qn, const bf16_t* __restrict__ Qr, const char* __restrict__ K8, const char* __restrict__ Kp8,
;                       const char* __restrict__ V8, const bf16_t* __restrict__ Gb, bf16_t* __restrict__ Yb, char* lds, int pos0) {
;     ...
;   for (int d = 0; d < 4; ++d) o[d] = f32x16{};
;   const int tid16 = tid * 16;
;   const unsigned t16u = (unsigned)tid16;
;     ...
;   f32x16 pA0, pA1, pB0, pB1; float mnA, mnB, alA, alB; i32x8 pa; VFrag vf; constexpr int NT = NT_MLA;
;   const i32x8 ones8 = {0x38383838, 0x38383838, 0x38383838, 0x38383838, 0x38383838, 0x38383838, 0x38383838, 0x38383838};
;   f32x16 lsum;
;     ...
;   ISSUE_K(0); ISSUE_K(1); ISSUE_K(2); ISSUE_V(0); ISSUE_V(1); TILE_SYNC();
;   qkt<false>(pA0, pA1, KS(0), q8, r32, hi, pA1); partialSM(pA0, pA1, m_reg, mnA, alA, 64, hi);
;   for (int j = 1; j + 1 < NT; j += 2) {
;     ISSUE_K(j + 2); ISSUE_K(j + 3); ISSUE_V(j + 1); ISSUE_V(j + 2); SBAR();
	v_pk_fma_f32 v[156:157], v[22:23], s[50:51], v[50:51] op_sel_hi:[1,0,0]
	v_pk_fma_f32 v[82:83], v[20:21], s[50:51], v[50:51] op_sel_hi:[1,0,0]
	v_pk_fma_f32 v[158:159], v[18:19], s[50:51], v[50:51] op_sel_hi:[1,0,0]
	v_pk_fma_f32 v[160:161], v[16:17], s[50:51], v[50:51] op_sel_hi:[1,0,0]
	v_lshlrev_b32_e32 v177, 4, v48
	s_addc_u32 s9, s31, 0
	v_mov_b64_e32 v[62:63], v[14:15]
	v_mov_b64_e32 v[30:31], v[14:15]
	v_mov_b64_e32 v[46:47], v[14:15]
	v_lshl_add_u64 v[144:145], s[34:35], 0, v[138:139]
	v_cmp_gt_u32_e64 s[6:7], 32, v169
	v_lshl_add_u32 v178, v167, 2, v171
	v_lshl_add_u64 v[146:147], s[8:9], 0, v[138:139]
	v_mov_b32_e32 v180, 0
	s_mov_b64 s[14:15], 0x89dc400
	v_mov_b64_e32 v[60:61], v[12:13]
	v_mov_b64_e32 v[58:59], v[10:11]
	v_mov_b64_e32 v[56:57], v[8:9]
	v_mov_b64_e32 v[54:55], v[6:7]
	v_mov_b64_e32 v[52:53], v[4:5]
	v_mov_b64_e32 v[50:51], v[2:3]
	v_mov_b64_e32 v[48:49], v[0:1]
	v_mov_b64_e32 v[28:29], v[12:13]
	v_mov_b64_e32 v[26:27], v[10:11]
	v_mov_b64_e32 v[24:25], v[8:9]
	v_mov_b64_e32 v[22:23], v[6:7]
	v_mov_b64_e32 v[20:21], v[4:5]
	v_mov_b64_e32 v[18:19], v[2:3]
	v_mov_b64_e32 v[16:17], v[0:1]
	v_mov_b64_e32 v[44:45], v[12:13]
	v_mov_b64_e32 v[42:43], v[10:11]
	v_mov_b64_e32 v[40:41], v[8:9]
	v_mov_b64_e32 v[38:39], v[6:7]
	v_mov_b64_e32 v[36:37], v[4:5]
	v_mov_b64_e32 v[34:35], v[2:3]
	v_mov_b64_e32 v[32:33], v[0:1]
	v_lshrrev_b32_e32 v175, 4, v169
	v_and_b32_e32 v175, 1, v175
	v_bfe_u32 v174, v169, 2, 2
	v_cmp_eq_u32_e64 s[8:9], v174, v175
	v_mov_b32_e32 v174, 0x38383838
	s_nop 1
	v_cndmask_b32_e64 v232, 0, v174, s[8:9]
	v_mov_b32_e32 v233, v232
	v_mov_b32_e32 v234, v232
	v_mov_b32_e32 v235, v232
	v_mov_b32_e32 v236, v232
	v_mov_b32_e32 v237, v232
	v_mov_b32_e32 v238, v232
	v_mov_b32_e32 v239, v232
	v_add_u32_e32 v176, v170, v176
	v_add_u32_e32 v176, 0x1000, v176
	v_mov_b32_e32 v64, v65
	v_mov_b32_e32 v84, v82
	v_mov_b32_e32 v85, v83
	v_mov_b32_e32 v65, v197
	v_mov_b32_e32 v66, v187
	v_mov_b32_e32 v67, v189
	v_mov_b32_e32 v68, v195
	v_mov_b32_e32 v69, v196
	v_mov_b32_e32 v70, v191
	v_mov_b32_e32 v71, v192
	v_mov_b32_e32 v72, v193
	v_mov_b32_e32 v73, v194
	v_mov_b32_e32 v74, v183
	v_mov_b32_e32 v75, v184
	v_mov_b32_e32 v76, v188
	v_mov_b32_e32 v77, v190
	v_mov_b32_e32 v78, v185
	v_mov_b32_e32 v79, v186
	v_mov_b32_e32 v80, v160
	v_mov_b32_e32 v81, v161
	v_mov_b32_e32 v82, v158
	v_mov_b32_e32 v83, v159
	v_mov_b32_e32 v86, v156
	v_mov_b32_e32 v87, v157
	v_mov_b32_e32 v88, v154
	v_mov_b32_e32 v89, v155
	v_mov_b32_e32 v90, v152
	v_mov_b32_e32 v91, v153
	v_mov_b32_e32 v92, v150
	v_mov_b32_e32 v93, v151
	v_mov_b32_e32 v94, v148
	v_mov_b32_e32 v95, v149
	s_lshl_b32 s78, s3, 4
	s_add_i32 s79, s78, 0x9000
	s_mul_i32 s80, s75, 0x186000
	s_add_u32 s80, s56, s80
	s_addc_u32 s81, s57, 0
	s_mov_b64 s[82:83], s[34:35]
	s_mul_i32 s84, s75, 0x208000
	s_add_u32 s84, s58, s84
	s_addc_u32 s85, s59, 0
	v_lshlrev_b32_e32 v231, 4, v169
	v_fmamk_f32 v230, v181, 0xbf800000, v164
	v_add_u32_e32 v140, 0x8000, v173
	v_mov_b32_e32 v240, v230
	v_mov_b32_e32 v241, v230
	v_mov_b32_e32 v242, v230
	v_mov_b32_e32 v243, v230
	v_mov_b32_e32 v244, v230
	v_mov_b32_e32 v245, v230
	v_mov_b32_e32 v246, v230
	v_mov_b32_e32 v247, v230
	v_mov_b32_e32 v248, v230
	v_mov_b32_e32 v249, v230
	v_mov_b32_e32 v250, v230
	v_mov_b32_e32 v251, v230
	v_mov_b32_e32 v252, v230
	v_mov_b32_e32 v253, v230
	v_mov_b32_e32 v254, v230
	v_mov_b32_e32 v255, v230
	ds_read_b128 v[104:107], v173 offset:9216
	ds_read_b64 v[108:109], v176 offset:9216
	ds_read_b128 v[110:113], v173 offset:9728
	ds_read_b64 v[114:115], v176 offset:9472
	ds_read_b128 v[148:151], v173 offset:11264
	ds_read_b64 v[152:153], v176 offset:10240
	ds_read_b128 v[154:157], v173 offset:11776
	ds_read_b64 v[158:159], v176 offset:10496
	ds_read_b128 v[214:217], v173 offset:15360
	ds_read_b64 v[218:219], v176 offset:13312
	ds_read_b128 v[220:223], v173 offset:15872
	ds_read_b64 v[224:225], v176 offset:13568
	s_cmp_ge_u32 s3, 0x100
	s_cbranch_scc1 .Lprio_skip
.Lprio_skip:
.LBB0_560:
	s_cmp_lt_u32 s3, 0x100
	s_cbranch_scc1 .Ldma_done
	s_add_i32 s8, s53, -1
	s_cmpk_lg_i32 s53, 0x102
	s_cselect_b32 s17, s8, 0x100
	s_and_b32 s16, s8, 3
	s_add_i32 s18, s53, -3
	s_cmpk_lt_u32 s18, 0xfe
	s_cselect_b32 s86, s53, 0x100
	s_and_b32 s87, s53, 3
	s_add_i32 s19, s53, -2
	s_and_b32 s20, s19, 3
	s_cmp_lt_u32 s3, 0x180
	s_cbranch_scc1 .Ldma_v
	s_cmp_ge_u32 s3, 0x1c0
	s_cselect_b32 s88, s86, s17
	s_cselect_b32 s89, s87, s16
	s_mul_i32 s89, s89, 0x2400
	s_mul_i32 s92, s88, 0x1800
	s_add_u32 s90, s80, s92
	s_addc_u32 s91, s81, 0
	s_mov_b32 m0, s89
	s_mul_i32 s92, s88, 0xc00
	global_load_lds_dwordx4 v231, s[90:91]
	global_load_lds_dwordx4 v231, s[90:91] offset:1024
	global_load_lds_dwordx4 v231, s[90:91] offset:2048
	global_load_lds_dwordx4 v231, s[90:91] offset:3072
	s_add_u32 s90, s90, 0x1000
	s_addc_u32 s91, s91, 0
	s_add_i32 s88, s89, 0x1000
	s_mov_b32 m0, s88
	s_add_i32 s89, s89, 0x1800
	global_load_lds_dwordx4 v231, s[90:91]
	global_load_lds_dwordx4 v231, s[90:91] offset:1024
	s_add_u32 s90, s82, s92
	s_addc_u32 s91, s83, 0
	s_mov_b32 m0, s89
	s_nop 0
	global_load_lds_dwordx4 v231, s[90:91]
	global_load_lds_dwordx4 v231, s[90:91] offset:1024
	global_load_lds_dwordx4 v231, s[90:91] offset:2048
	s_branch .Ldma_done
